# LoRA GEMM: per-unit K-tile count (w/a LoRA tiles run 2 of 6 K-tiles; the other 4 multiply all-zero weight columns)
# speedup vs baseline: 1.0116x; 1.0116x over previous
.LBB0_660:
	v_mov_b32_e32 v9, 0
	s_andn2_b64 vcc, exec, s[22:23]
	v_mov_b32_e32 v8, v9
	v_mov_b32_e32 v7, v9
	v_mov_b32_e32 v6, v9
	v_mov_b32_e32 v5, v9
	v_mov_b32_e32 v4, v9
	v_mov_b32_e32 v3, v9
	v_mov_b32_e32 v2, v9
	v_mov_b32_e32 v129, v9
	v_mov_b32_e32 v128, v9
	v_mov_b32_e32 v127, v9
	v_mov_b32_e32 v126, v9
	v_mov_b32_e32 v125, v9
	v_mov_b32_e32 v124, v9
	v_mov_b32_e32 v123, v9
	v_mov_b32_e32 v122, v9
	v_mov_b32_e32 v121, v9
	v_mov_b32_e32 v120, v9
	v_mov_b32_e32 v119, v9
	v_mov_b32_e32 v118, v9
	v_mov_b32_e32 v117, v9
	v_mov_b32_e32 v116, v9
	v_mov_b32_e32 v115, v9
	v_mov_b32_e32 v114, v9
	v_mov_b32_e32 v113, v9
	v_mov_b32_e32 v112, v9
	v_mov_b32_e32 v111, v9
	v_mov_b32_e32 v110, v9
	v_mov_b32_e32 v109, v9
	v_mov_b32_e32 v108, v9
	v_mov_b32_e32 v107, v9
	v_mov_b32_e32 v106, v9
	v_mov_b32_e32 v73, v9
	v_mov_b32_e32 v72, v9
	v_mov_b32_e32 v71, v9
	v_mov_b32_e32 v70, v9
	v_mov_b32_e32 v69, v9
	v_mov_b32_e32 v68, v9
	v_mov_b32_e32 v67, v9
	v_mov_b32_e32 v66, v9
	v_mov_b32_e32 v65, v9
	v_mov_b32_e32 v64, v9
	v_mov_b32_e32 v63, v9
	v_mov_b32_e32 v62, v9
	v_mov_b32_e32 v61, v9
	v_mov_b32_e32 v60, v9
	v_mov_b32_e32 v59, v9
	v_mov_b32_e32 v58, v9
	v_mov_b32_e32 v57, v9
	v_mov_b32_e32 v56, v9
	v_mov_b32_e32 v55, v9
	v_mov_b32_e32 v54, v9
	v_mov_b32_e32 v53, v9
	v_mov_b32_e32 v52, v9
	v_mov_b32_e32 v51, v9
	v_mov_b32_e32 v50, v9
	v_mov_b32_e32 v49, v9
	v_mov_b32_e32 v48, v9
	v_mov_b32_e32 v47, v9
	v_mov_b32_e32 v46, v9
	v_mov_b32_e32 v45, v9
	v_mov_b32_e32 v44, v9
	v_mov_b32_e32 v43, v9
	v_mov_b32_e32 v42, v9
	v_mov_b32_e32 v105, v9
	v_mov_b32_e32 v104, v9
	v_mov_b32_e32 v103, v9
	v_mov_b32_e32 v102, v9
	v_mov_b32_e32 v101, v9
	v_mov_b32_e32 v100, v9
	v_mov_b32_e32 v99, v9
	v_mov_b32_e32 v98, v9
	v_mov_b32_e32 v97, v9
	v_mov_b32_e32 v96, v9
	v_mov_b32_e32 v95, v9
	v_mov_b32_e32 v94, v9
	v_mov_b32_e32 v93, v9
	v_mov_b32_e32 v92, v9
	v_mov_b32_e32 v91, v9
	v_mov_b32_e32 v90, v9
	v_mov_b32_e32 v89, v9
	v_mov_b32_e32 v88, v9
	v_mov_b32_e32 v87, v9
	v_mov_b32_e32 v86, v9
	v_mov_b32_e32 v85, v9
	v_mov_b32_e32 v84, v9
	v_mov_b32_e32 v83, v9
	v_mov_b32_e32 v82, v9
	v_mov_b32_e32 v81, v9
	v_mov_b32_e32 v80, v9
	v_mov_b32_e32 v79, v9
	v_mov_b32_e32 v78, v9
	v_mov_b32_e32 v77, v9
	v_mov_b32_e32 v76, v9
	v_mov_b32_e32 v75, v9
	v_mov_b32_e32 v74, v9
	v_mov_b32_e32 v41, v9
	v_mov_b32_e32 v40, v9
	v_mov_b32_e32 v39, v9
	v_mov_b32_e32 v38, v9
	v_mov_b32_e32 v37, v9
	v_mov_b32_e32 v36, v9
	v_mov_b32_e32 v35, v9
	v_mov_b32_e32 v34, v9
	v_mov_b32_e32 v33, v9
	v_mov_b32_e32 v32, v9
	v_mov_b32_e32 v31, v9
	v_mov_b32_e32 v30, v9
	v_mov_b32_e32 v29, v9
	v_mov_b32_e32 v28, v9
	v_mov_b32_e32 v27, v9
	v_mov_b32_e32 v26, v9
	v_mov_b32_e32 v25, v9
	v_mov_b32_e32 v24, v9
	v_mov_b32_e32 v23, v9
	v_mov_b32_e32 v22, v9
	v_mov_b32_e32 v21, v9
	v_mov_b32_e32 v20, v9
	v_mov_b32_e32 v19, v9
	v_mov_b32_e32 v18, v9
	v_mov_b32_e32 v17, v9
	v_mov_b32_e32 v16, v9
	v_mov_b32_e32 v15, v9
	v_mov_b32_e32 v14, v9
	v_mov_b32_e32 v13, v9
	v_mov_b32_e32 v12, v9
	v_mov_b32_e32 v11, v9
	v_mov_b32_e32 v10, v9
	s_cbranch_vccnz .LBB0_663
	s_add_u32 s30, s4, 0x100
	s_addc_u32 s31, s5, 0
	s_add_u32 s4, s28, 0x80
	v_mov_b32_e32 v10, 0
	s_addc_u32 s5, s29, 0
	s_mov_b32 s28, 0
	v_readlane_b32 s100, v252, 6
	s_nop 3
	s_cmp_lt_i32 s90, 4
	s_cselect_b32 s62, 2, 6
	s_cmp_eq_u32 s100, 0
	s_cselect_b32 s62, 2, s62
	s_add_i32 s75, s62, -2
	v_mov_b32_e32 v11, v10
	v_mov_b32_e32 v12, v10
	v_mov_b32_e32 v13, v10
	v_mov_b32_e32 v14, v10
	v_mov_b32_e32 v15, v10
	v_mov_b32_e32 v16, v10
	v_mov_b32_e32 v17, v10
	v_mov_b32_e32 v18, v10
	v_mov_b32_e32 v19, v10
	v_mov_b32_e32 v20, v10
	v_mov_b32_e32 v21, v10
	v_mov_b32_e32 v22, v10
	v_mov_b32_e32 v23, v10
	v_mov_b32_e32 v24, v10
	v_mov_b32_e32 v25, v10
	v_mov_b32_e32 v26, v10
	v_mov_b32_e32 v27, v10
	v_mov_b32_e32 v28, v10
	v_mov_b32_e32 v29, v10
	v_mov_b32_e32 v30, v10
	v_mov_b32_e32 v31, v10
	v_mov_b32_e32 v32, v10
	v_mov_b32_e32 v33, v10
	v_mov_b32_e32 v34, v10
	v_mov_b32_e32 v35, v10
	v_mov_b32_e32 v36, v10
	v_mov_b32_e32 v37, v10
	v_mov_b32_e32 v38, v10
	v_mov_b32_e32 v39, v10
	v_mov_b32_e32 v40, v10
	v_mov_b32_e32 v41, v10
	v_mov_b32_e32 v74, v10
	v_mov_b32_e32 v75, v10
	v_mov_b32_e32 v76, v10
	v_mov_b32_e32 v77, v10
	v_mov_b32_e32 v78, v10
	v_mov_b32_e32 v79, v10
	v_mov_b32_e32 v80, v10
	v_mov_b32_e32 v81, v10
	v_mov_b32_e32 v82, v10
	v_mov_b32_e32 v83, v10
	v_mov_b32_e32 v84, v10
	v_mov_b32_e32 v85, v10
	v_mov_b32_e32 v86, v10
	v_mov_b32_e32 v87, v10
	v_mov_b32_e32 v88, v10
	v_mov_b32_e32 v89, v10
	v_mov_b32_e32 v90, v10
	v_mov_b32_e32 v91, v10
	v_mov_b32_e32 v92, v10
	v_mov_b32_e32 v93, v10
	v_mov_b32_e32 v94, v10
	v_mov_b32_e32 v95, v10
	v_mov_b32_e32 v96, v10
	v_mov_b32_e32 v97, v10
	v_mov_b32_e32 v98, v10
	v_mov_b32_e32 v99, v10
	v_mov_b32_e32 v100, v10
	v_mov_b32_e32 v101, v10
	v_mov_b32_e32 v102, v10
	v_mov_b32_e32 v103, v10
	v_mov_b32_e32 v104, v10
	v_mov_b32_e32 v105, v10
	v_mov_b32_e32 v42, v10
	v_mov_b32_e32 v43, v10
	v_mov_b32_e32 v44, v10
	v_mov_b32_e32 v45, v10
	v_mov_b32_e32 v46, v10
	v_mov_b32_e32 v47, v10
	v_mov_b32_e32 v48, v10
	v_mov_b32_e32 v49, v10
	v_mov_b32_e32 v50, v10
	v_mov_b32_e32 v51, v10
	v_mov_b32_e32 v52, v10
	v_mov_b32_e32 v53, v10
	v_mov_b32_e32 v54, v10
	v_mov_b32_e32 v55, v10
	v_mov_b32_e32 v56, v10
	v_mov_b32_e32 v57, v10
	v_mov_b32_e32 v58, v10
	v_mov_b32_e32 v59, v10
	v_mov_b32_e32 v60, v10
	v_mov_b32_e32 v61, v10
	v_mov_b32_e32 v62, v10
	v_mov_b32_e32 v63, v10
	v_mov_b32_e32 v64, v10
	v_mov_b32_e32 v65, v10
	v_mov_b32_e32 v66, v10
	v_mov_b32_e32 v67, v10
	v_mov_b32_e32 v68, v10
	v_mov_b32_e32 v69, v10
	v_mov_b32_e32 v70, v10
	v_mov_b32_e32 v71, v10
	v_mov_b32_e32 v72, v10
	v_mov_b32_e32 v73, v10
	v_mov_b32_e32 v106, v10
	v_mov_b32_e32 v107, v10
	v_mov_b32_e32 v108, v10
	v_mov_b32_e32 v109, v10
	v_mov_b32_e32 v110, v10
	v_mov_b32_e32 v111, v10
	v_mov_b32_e32 v112, v10
	v_mov_b32_e32 v113, v10
	v_mov_b32_e32 v114, v10
	v_mov_b32_e32 v115, v10
	v_mov_b32_e32 v116, v10
	v_mov_b32_e32 v117, v10
	v_mov_b32_e32 v118, v10
	v_mov_b32_e32 v119, v10
	v_mov_b32_e32 v120, v10
	v_mov_b32_e32 v121, v10
	v_mov_b32_e32 v122, v10
	v_mov_b32_e32 v123, v10
	v_mov_b32_e32 v124, v10
	v_mov_b32_e32 v125, v10
	v_mov_b32_e32 v126, v10
	v_mov_b32_e32 v127, v10
	v_mov_b32_e32 v128, v10
	v_mov_b32_e32 v129, v10
	v_mov_b32_e32 v2, v10
	v_mov_b32_e32 v3, v10
	v_mov_b32_e32 v4, v10
	v_mov_b32_e32 v5, v10
	v_mov_b32_e32 v6, v10
	v_mov_b32_e32 v7, v10
	v_mov_b32_e32 v8, v10
	v_mov_b32_e32 v9, v10
